# barrier: XCD leaders no longer wait for the acknowledgements of their 16 arrival atomics before the first poll
# baseline (speedup 1.0000x reference)
; __device__ __forceinline__ unsigned xb_ld(unsigned* p)              { return __hip_atomic_load(p, __ATOMIC_RELAXED, __HIP_MEMORY_SCOPE_AGENT); }
; __device__ __forceinline__ unsigned xb_add(unsigned* p, unsigned v) { return __hip_atomic_fetch_add(p, v, __ATOMIC_RELAXED, __HIP_MEMORY_SCOPE_AGENT); }
; #define XB_SPIN(cond, bar) do { unsigned _sp = 0; while (cond) { __builtin_amdgcn_s_sleep(1); \
;     if ((++_sp & 255u) == 0u) { if (xb_ld(&(bar)[XB_TMO])) break; if (_sp > XB_SPIN_CAP) { atomicAdd(&(bar)[XB_TMO], 1u); break; } } } } while (0)
; __device__ __forceinline__ void xcd_barrier(const XcdBarrier& b) {
;     ...
;         const unsigned old = xb_add(&bar[XB_XSUB(b.x)], 1u);
;         const unsigned gen = old / nloc;
;         if (old + 1u == (gen + 1u) * nloc) {
;             __builtin_amdgcn_fence(__ATOMIC_RELEASE, "agent");
;             asm volatile("s_waitcnt vmcnt(0)" ::: "memory");
;             const unsigned og = xb_add(&bar[XB_TOP], 1u);
;             const unsigned tg = og / nx;
;             if (og + 1u == (tg + 1u) * nx) xb_add(&bar[XB_TOPGEN], 1u);
;             else XB_SPIN(xb_ld(&bar[XB_TOPGEN]) == tg, bar);
;             __builtin_amdgcn_fence(__ATOMIC_ACQUIRE, "agent");
.LBB0_162:
	s_or_b64 exec, exec, s[10:11]
	v_cvt_f32_u32_e32 v4, v1
	v_readfirstlane_b32 s8, v3
	s_add_i32 s10, s28, 0x900
	s_mov_b32 s11, 0
	s_lshl_b64 s[10:11], s[10:11], 2
	s_add_u32 s10, s26, s10
	s_addc_u32 s11, s27, s11
	v_rcp_iflag_f32_e32 v4, v4
	v_add_u32_e32 v2, s8, v2
	v_add_u32_e32 v5, 1, v2
	s_mov_b64 s[12:13], -1
	v_mul_f32_e32 v3, 0x4f7ffffe, v4
	v_cvt_u32_f32_e32 v3, v3
	v_sub_u32_e32 v4, 0, v1
	v_mul_lo_u32 v4, v4, v3
	v_mul_hi_u32 v4, v3, v4
	v_add_u32_e32 v3, v3, v4
	v_mul_hi_u32 v3, v2, v3
	v_mul_lo_u32 v4, v3, v1
	v_sub_u32_e32 v2, v2, v4
	v_add_u32_e32 v6, 1, v3
	v_cmp_ge_u32_e32 vcc, v2, v1
	v_sub_u32_e32 v4, v2, v1
	s_nop 0
	v_cndmask_b32_e32 v3, v3, v6, vcc
	v_cndmask_b32_e32 v2, v2, v4, vcc
	v_add_u32_e32 v4, 1, v3
	v_cmp_ge_u32_e32 vcc, v2, v1
	s_nop 1
	v_cndmask_b32_e32 v4, v3, v4, vcc
	v_mul_lo_u32 v2, v1, v4
	v_add_u32_e32 v1, v2, v1
	v_cmp_eq_u32_e32 vcc, v1, v1
	v_mov_b64_e32 v[2:3], s[10:11]
	s_and_saveexec_b64 s[8:9], vcc
	s_cbranch_execz .LBB0_174
	v_mov_b32_e32 v1, 0
	global_load_dword v2, v1, s[10:11] sc1
	s_mov_b64 s[16:17], 0
	s_waitcnt vmcnt(0)
	v_cmp_lt_u32_e32 vcc, v2, v255
	s_and_saveexec_b64 s[14:15], vcc
	s_cbranch_execz .LBB0_173
	s_add_u32 s12, s6, 0xc0200
	s_addc_u32 s13, s7, 0
	s_mov_b32 s24, 1
	s_mov_b64 s[6:7], 0
	s_branch .LBB0_166

; __device__ __forceinline__ unsigned xb_ld(unsigned* p)              { return __hip_atomic_load(p, __ATOMIC_RELAXED, __HIP_MEMORY_SCOPE_AGENT); }
; __device__ __forceinline__ unsigned xb_add(unsigned* p, unsigned v) { return __hip_atomic_fetch_add(p, v, __ATOMIC_RELAXED, __HIP_MEMORY_SCOPE_AGENT); }
; #define XB_SPIN(cond, bar) do { unsigned _sp = 0; while (cond) { __builtin_amdgcn_s_sleep(1); \
;     if ((++_sp & 255u) == 0u) { if (xb_ld(&(bar)[XB_TMO])) break; if (_sp > XB_SPIN_CAP) { atomicAdd(&(bar)[XB_TMO], 1u); break; } } } } while (0)
; __device__ __forceinline__ void xcd_barrier(const XcdBarrier& b) {
;     ...
;         const unsigned old = xb_add(&bar[XB_XSUB(b.x)], 1u);
;         const unsigned gen = old / nloc;
;         if (old + 1u == (gen + 1u) * nloc) {
;             __builtin_amdgcn_fence(__ATOMIC_RELEASE, "agent");
;             asm volatile("s_waitcnt vmcnt(0)" ::: "memory");
;             const unsigned og = xb_add(&bar[XB_TOP], 1u);
;             const unsigned tg = og / nx;
;             if (og + 1u == (tg + 1u) * nx) xb_add(&bar[XB_TOPGEN], 1u);
;             else XB_SPIN(xb_ld(&bar[XB_TOPGEN]) == tg, bar);
;             __builtin_amdgcn_fence(__ATOMIC_ACQUIRE, "agent");
.LBB0_272:
	s_or_b64 exec, exec, s[10:11]
	v_cvt_f32_u32_e32 v5, v2
	v_readfirstlane_b32 s8, v4
	s_add_i32 s10, s28, 0x900
	s_mov_b32 s11, 0
	s_lshl_b64 s[10:11], s[10:11], 2
	s_add_u32 s10, s26, s10
	s_addc_u32 s11, s27, s11
	v_rcp_iflag_f32_e32 v5, v5
	v_add_u32_e32 v3, s8, v3
	v_add_u32_e32 v6, 1, v3
	s_mov_b64 s[12:13], -1
	v_mul_f32_e32 v4, 0x4f7ffffe, v5
	v_cvt_u32_f32_e32 v4, v4
	v_sub_u32_e32 v5, 0, v2
	v_mul_lo_u32 v5, v5, v4
	v_mul_hi_u32 v5, v4, v5
	v_add_u32_e32 v4, v4, v5
	v_mul_hi_u32 v4, v3, v4
	v_mul_lo_u32 v5, v4, v2
	v_sub_u32_e32 v3, v3, v5
	v_add_u32_e32 v7, 1, v4
	v_cmp_ge_u32_e32 vcc, v3, v2
	v_sub_u32_e32 v5, v3, v2
	s_nop 0
	v_cndmask_b32_e32 v4, v4, v7, vcc
	v_cndmask_b32_e32 v3, v3, v5, vcc
	v_add_u32_e32 v5, 1, v4
	v_cmp_ge_u32_e32 vcc, v3, v2
	s_nop 1
	v_cndmask_b32_e32 v4, v4, v5, vcc
	v_mul_lo_u32 v3, v2, v4
	v_add_u32_e32 v2, v3, v2
	v_cmp_eq_u32_e32 vcc, v2, v2
	v_mov_b64_e32 v[2:3], s[10:11]
	s_and_saveexec_b64 s[8:9], vcc
	s_cbranch_execz .LBB0_284
	v_mov_b32_e32 v2, 0
	global_load_dword v3, v2, s[10:11] sc1
	s_mov_b64 s[16:17], 0
	s_waitcnt vmcnt(0)
	v_cmp_lt_u32_e32 vcc, v3, v255
	s_and_saveexec_b64 s[14:15], vcc
	s_cbranch_execz .LBB0_283
	s_add_u32 s12, s6, 0xc0200
	s_addc_u32 s13, s7, 0
	s_mov_b32 s24, 1
	s_mov_b64 s[6:7], 0
	s_branch .LBB0_276

; __device__ __forceinline__ unsigned xb_ld(unsigned* p)              { return __hip_atomic_load(p, __ATOMIC_RELAXED, __HIP_MEMORY_SCOPE_AGENT); }
; __device__ __forceinline__ unsigned xb_add(unsigned* p, unsigned v) { return __hip_atomic_fetch_add(p, v, __ATOMIC_RELAXED, __HIP_MEMORY_SCOPE_AGENT); }
; #define XB_SPIN(cond, bar) do { unsigned _sp = 0; while (cond) { __builtin_amdgcn_s_sleep(1); \
;     if ((++_sp & 255u) == 0u) { if (xb_ld(&(bar)[XB_TMO])) break; if (_sp > XB_SPIN_CAP) { atomicAdd(&(bar)[XB_TMO], 1u); break; } } } } while (0)
; __device__ __forceinline__ void xcd_barrier(const XcdBarrier& b) {
;     ...
;         const unsigned old = xb_add(&bar[XB_XSUB(b.x)], 1u);
;         const unsigned gen = old / nloc;
;         if (old + 1u == (gen + 1u) * nloc) {
;             __builtin_amdgcn_fence(__ATOMIC_RELEASE, "agent");
;             asm volatile("s_waitcnt vmcnt(0)" ::: "memory");
;             const unsigned og = xb_add(&bar[XB_TOP], 1u);
;             const unsigned tg = og / nx;
;             if (og + 1u == (tg + 1u) * nx) xb_add(&bar[XB_TOPGEN], 1u);
;             else XB_SPIN(xb_ld(&bar[XB_TOPGEN]) == tg, bar);
;             __builtin_amdgcn_fence(__ATOMIC_ACQUIRE, "agent");
.LBB0_1636:
	s_or_b64 exec, exec, s[16:17]
	v_cvt_f32_u32_e32 v5, v2
	v_readfirstlane_b32 s10, v4
	s_add_i32 s16, s36, 0x900
	s_mov_b32 s17, 0
	s_lshl_b64 s[16:17], s[16:17], 2
	s_add_u32 s16, s34, s16
	s_addc_u32 s17, s35, s17
	v_rcp_iflag_f32_e32 v5, v5
	v_add_u32_e32 v3, s10, v3
	v_add_u32_e32 v6, 1, v3
	s_mov_b64 s[18:19], -1
	v_mul_f32_e32 v4, 0x4f7ffffe, v5
	v_cvt_u32_f32_e32 v4, v4
	v_sub_u32_e32 v5, 0, v2
	v_mul_lo_u32 v5, v5, v4
	v_mul_hi_u32 v5, v4, v5
	v_add_u32_e32 v4, v4, v5
	v_mul_hi_u32 v4, v3, v4
	v_mul_lo_u32 v5, v4, v2
	v_sub_u32_e32 v3, v3, v5
	v_add_u32_e32 v7, 1, v4
	v_cmp_ge_u32_e32 vcc, v3, v2
	v_sub_u32_e32 v5, v3, v2
	s_nop 0
	v_cndmask_b32_e32 v4, v4, v7, vcc
	v_cndmask_b32_e32 v3, v3, v5, vcc
	v_add_u32_e32 v5, 1, v4
	v_cmp_ge_u32_e32 vcc, v3, v2
	s_nop 1
	v_cndmask_b32_e32 v4, v4, v5, vcc
	v_mul_lo_u32 v3, v2, v4
	v_add_u32_e32 v2, v3, v2
	v_cmp_eq_u32_e32 vcc, v2, v2
	v_mov_b64_e32 v[2:3], s[16:17]
	s_and_saveexec_b64 s[10:11], vcc
	s_cbranch_execz .LBB0_1648
	v_mov_b32_e32 v2, 0
	global_load_dword v3, v2, s[16:17] sc1
	s_mov_b64 s[22:23], 0
	s_waitcnt vmcnt(0)
	v_cmp_lt_u32_e32 vcc, v3, v255
	s_and_saveexec_b64 s[20:21], vcc
	s_cbranch_execz .LBB0_1647
	s_add_u32 s18, s8, 0xc0200
	s_addc_u32 s19, s9, 0
	s_mov_b32 s30, 1
	s_mov_b64 s[8:9], 0
	s_branch .LBB0_1640

; __device__ __forceinline__ unsigned xb_ld(unsigned* p)              { return __hip_atomic_load(p, __ATOMIC_RELAXED, __HIP_MEMORY_SCOPE_AGENT); }
; __device__ __forceinline__ unsigned xb_add(unsigned* p, unsigned v) { return __hip_atomic_fetch_add(p, v, __ATOMIC_RELAXED, __HIP_MEMORY_SCOPE_AGENT); }
; #define XB_SPIN(cond, bar) do { unsigned _sp = 0; while (cond) { __builtin_amdgcn_s_sleep(1); \
;     if ((++_sp & 255u) == 0u) { if (xb_ld(&(bar)[XB_TMO])) break; if (_sp > XB_SPIN_CAP) { atomicAdd(&(bar)[XB_TMO], 1u); break; } } } } while (0)
; __device__ __forceinline__ void xcd_barrier(const XcdBarrier& b) {
;     ...
;         const unsigned old = xb_add(&bar[XB_XSUB(b.x)], 1u);
;         const unsigned gen = old / nloc;
;         if (old + 1u == (gen + 1u) * nloc) {
;             __builtin_amdgcn_fence(__ATOMIC_RELEASE, "agent");
;             asm volatile("s_waitcnt vmcnt(0)" ::: "memory");
;             const unsigned og = xb_add(&bar[XB_TOP], 1u);
;             const unsigned tg = og / nx;
;             if (og + 1u == (tg + 1u) * nx) xb_add(&bar[XB_TOPGEN], 1u);
;             else XB_SPIN(xb_ld(&bar[XB_TOPGEN]) == tg, bar);
;             __builtin_amdgcn_fence(__ATOMIC_ACQUIRE, "agent");
.LBB0_3190:
	s_or_b64 exec, exec, s[10:11]
	v_cvt_f32_u32_e32 v5, v2
	v_readfirstlane_b32 s8, v4
	s_add_i32 s10, s30, 0x900
	s_mov_b32 s11, 0
	s_lshl_b64 s[10:11], s[10:11], 2
	s_add_u32 s10, s28, s10
	s_addc_u32 s11, s29, s11
	v_rcp_iflag_f32_e32 v5, v5
	v_add_u32_e32 v3, s8, v3
	v_add_u32_e32 v6, 1, v3
	s_mov_b64 s[14:15], -1
	v_mul_f32_e32 v4, 0x4f7ffffe, v5
	v_cvt_u32_f32_e32 v4, v4
	v_sub_u32_e32 v5, 0, v2
	v_mul_lo_u32 v5, v5, v4
	v_mul_hi_u32 v5, v4, v5
	v_add_u32_e32 v4, v4, v5
	v_mul_hi_u32 v4, v3, v4
	v_mul_lo_u32 v5, v4, v2
	v_sub_u32_e32 v3, v3, v5
	v_add_u32_e32 v7, 1, v4
	v_cmp_ge_u32_e32 vcc, v3, v2
	v_sub_u32_e32 v5, v3, v2
	s_nop 0
	v_cndmask_b32_e32 v4, v4, v7, vcc
	v_cndmask_b32_e32 v3, v3, v5, vcc
	v_add_u32_e32 v5, 1, v4
	v_cmp_ge_u32_e32 vcc, v3, v2
	s_nop 1
	v_cndmask_b32_e32 v4, v4, v5, vcc
	v_mul_lo_u32 v3, v2, v4
	v_add_u32_e32 v2, v3, v2
	v_cmp_eq_u32_e32 vcc, v2, v2
	v_mov_b64_e32 v[2:3], s[10:11]
	s_and_saveexec_b64 s[8:9], vcc
	s_cbranch_execz .LBB0_3202
	v_mov_b32_e32 v2, 0
	global_load_dword v3, v2, s[10:11] sc1
	s_mov_b64 s[18:19], 0
	s_waitcnt vmcnt(0)
	v_cmp_lt_u32_e32 vcc, v3, v255
	s_and_saveexec_b64 s[16:17], vcc
	s_cbranch_execz .LBB0_3201
	s_add_u32 s14, s6, 0xc0200
	s_addc_u32 s15, s7, 0
	s_mov_b32 s26, 1
	s_mov_b64 s[6:7], 0
	s_branch .LBB0_3194
